# LRU passes 1 and 2: u-value LDS reads hoisted ahead of the gate math (fewer LDS round-trip waits)
# baseline (speedup 1.0000x reference)
.LBB0_301:
	s_waitcnt lgkmcnt(0)
	s_barrier
	ds_read_b128 v[110:113], v135
	ds_read_b128 v[114:117], v135 offset:4352
	ds_read_b128 v[122:125], v135 offset:8704
	ds_read_b128 v[194:197], v135 offset:13056
	s_waitcnt lgkmcnt(3)
	v_mfma_f32_16x16x32_bf16 v[118:121], v[110:113], v[0:3], 0
	v_mfma_f32_16x16x32_bf16 v[110:113], v[110:113], v[8:11], 0
	ds_read_b128 v[206:209], v135 offset:64
	s_waitcnt lgkmcnt(3)
	v_mfma_f32_16x16x32_bf16 v[198:201], v[114:117], v[0:3], 0
	v_mfma_f32_16x16x32_bf16 v[114:117], v[114:117], v[8:11], 0
	ds_read_b128 v[214:217], v135 offset:4416
	s_waitcnt lgkmcnt(3)
	v_mfma_f32_16x16x32_bf16 v[210:213], v[122:125], v[0:3], 0
	v_mfma_f32_16x16x32_bf16 v[122:125], v[122:125], v[8:11], 0
	ds_read_b128 v[222:225], v135 offset:8768
	s_waitcnt lgkmcnt(3)
	v_mfma_f32_16x16x32_bf16 v[218:221], v[194:197], v[0:3], 0
	v_mfma_f32_16x16x32_bf16 v[194:197], v[194:197], v[8:11], 0
	ds_read_b128 v[226:229], v135 offset:13120
	s_waitcnt lgkmcnt(3)
	v_mfma_f32_16x16x32_bf16 v[118:121], v[206:209], v[4:7], v[118:121]
	v_mfma_f32_16x16x32_bf16 v[110:113], v[206:209], v[12:15], v[110:113]
	ds_read_b128 v[206:209], v135 offset:128
	s_waitcnt lgkmcnt(3)
	v_mfma_f32_16x16x32_bf16 v[198:201], v[214:217], v[4:7], v[198:201]
	v_mfma_f32_16x16x32_bf16 v[114:117], v[214:217], v[12:15], v[114:117]
	ds_read_b128 v[214:217], v135 offset:4480
	s_waitcnt lgkmcnt(3)
	v_mfma_f32_16x16x32_bf16 v[210:213], v[222:225], v[4:7], v[210:213]
	v_mfma_f32_16x16x32_bf16 v[122:125], v[222:225], v[12:15], v[122:125]
	ds_read_b128 v[222:225], v135 offset:8832
	s_waitcnt lgkmcnt(3)
	v_mfma_f32_16x16x32_bf16 v[218:221], v[226:229], v[4:7], v[218:221]
	v_mfma_f32_16x16x32_bf16 v[194:197], v[226:229], v[12:15], v[194:197]
	ds_read_b128 v[226:229], v135 offset:13184
	s_waitcnt lgkmcnt(3)
	v_mfma_f32_16x16x32_bf16 v[118:121], v[206:209], v[16:19], v[118:121]
	v_mfma_f32_16x16x32_bf16 v[110:113], v[206:209], v[28:31], v[110:113]
	ds_read_b128 v[206:209], v135 offset:192
	s_waitcnt lgkmcnt(3)
	v_mfma_f32_16x16x32_bf16 v[198:201], v[214:217], v[16:19], v[198:201]
	v_mfma_f32_16x16x32_bf16 v[114:117], v[214:217], v[28:31], v[114:117]
	ds_read_b128 v[214:217], v135 offset:4544
	s_waitcnt lgkmcnt(3)
	v_mfma_f32_16x16x32_bf16 v[210:213], v[222:225], v[16:19], v[210:213]
	v_mfma_f32_16x16x32_bf16 v[222:225], v[222:225], v[28:31], v[122:125]
	ds_read_b128 v[230:233], v135 offset:8896
	s_waitcnt lgkmcnt(3)
	v_mfma_f32_16x16x32_bf16 v[218:221], v[226:229], v[16:19], v[218:221]
	v_mfma_f32_16x16x32_bf16 v[194:197], v[226:229], v[28:31], v[194:197]
	ds_read_b128 v[234:237], v135 offset:13248
	s_waitcnt lgkmcnt(3)
	v_mfma_f32_16x16x32_bf16 v[226:229], v[206:209], v[20:23], v[118:121]
	v_mfma_f32_16x16x32_bf16 v[206:209], v[206:209], v[32:35], v[110:113]
	s_waitcnt lgkmcnt(2)
	v_mfma_f32_16x16x32_bf16 v[198:201], v[214:217], v[20:23], v[198:201]
	v_mfma_f32_16x16x32_bf16 v[214:217], v[214:217], v[32:35], v[114:117]
	s_waitcnt lgkmcnt(1)
	v_mfma_f32_16x16x32_bf16 v[122:125], v[230:233], v[20:23], v[210:213]
	v_mfma_f32_16x16x32_bf16 v[118:121], v[230:233], v[32:35], v[222:225]
	s_waitcnt lgkmcnt(0)
	v_mfma_f32_16x16x32_bf16 v[114:117], v[234:237], v[20:23], v[218:221]
	v_mfma_f32_16x16x32_bf16 v[110:113], v[234:237], v[32:35], v[194:197]
	ds_read2st64_b32 v[238:239], v139 offset0:68 offset1:70
	ds_read2st64_b32 v[240:241], v139 offset0:72 offset1:74
	ds_read2st64_b32 v[242:243], v139 offset0:100 offset1:102
	ds_read2st64_b32 v[244:245], v139 offset0:104 offset1:106
	ds_read2st64_b32 v[246:247], v139 offset0:132 offset1:134
	ds_read2st64_b32 v[248:249], v139 offset0:136 offset1:138
	ds_read2st64_b32 v[250:251], v139 offset0:164 offset1:166
	ds_read2st64_b32 v[252:253], v139 offset0:168 offset1:170
	s_nop 2
	v_fma_f32 v194, -v226, s4, v90
	v_fma_f32 v195, -v227, s4, v91
	v_pk_fma_f32 v[196:197], v[206:207], s[4:5], v[128:129] op_sel_hi:[1,0,1] neg_lo:[1,0,0] neg_hi:[1,0,0]
	v_exp_f32_e32 v194, v194
	v_exp_f32_e32 v195, v195
	v_exp_f32_e32 v196, v196
	v_exp_f32_e32 v197, v197
	v_pk_add_f32 v[194:195], v[194:195], 1.0 op_sel_hi:[1,0]
	v_pk_fma_f32 v[210:211], v[228:229], s[4:5], v[90:91] op_sel_hi:[1,0,1] neg_lo:[1,0,0] neg_hi:[1,0,0]
	v_rcp_f32_e32 v194, v194
	v_rcp_f32_e32 v195, v195
	v_pk_add_f32 v[196:197], v[196:197], 1.0 op_sel_hi:[1,0]
	v_pk_fma_f32 v[198:199], v[198:199], s[4:5], v[90:91] op_sel_hi:[1,0,1] neg_lo:[1,0,0] neg_hi:[1,0,0]
	v_rcp_f32_e32 v196, v196
	v_pk_mul_f32 v[194:195], v[130:131], v[194:195]
	v_rcp_f32_e32 v197, v197
	v_exp_f32_e32 v194, v194
	v_exp_f32_e32 v195, v195
	v_exp_f32_e32 v198, v198
	v_exp_f32_e32 v199, v199
	v_pk_fma_f32 v[200:201], v[200:201], s[4:5], v[90:91] op_sel_hi:[1,0,1] neg_lo:[1,0,0] neg_hi:[1,0,0]
	v_pk_fma_f32 v[202:203], v[194:195], v[194:195], 1.0 op_sel_hi:[1,1,0] neg_lo:[1,0,0] neg_hi:[1,0,0]
	v_exp_f32_e32 v200, v200
	v_sqrt_f32_e32 v202, v202
	v_sqrt_f32_e32 v203, v203
	v_exp_f32_e32 v201, v201
	v_pk_fma_f32 v[122:123], v[122:123], s[4:5], v[90:91] op_sel_hi:[1,0,1] neg_lo:[1,0,0] neg_hi:[1,0,0]
	v_pk_fma_f32 v[118:119], v[118:119], s[4:5], v[128:129] op_sel_hi:[1,0,1] neg_lo:[1,0,0] neg_hi:[1,0,0]
	v_pk_mul_f32 v[196:197], v[196:197], v[202:203]
	v_exp_f32_e32 v202, v210
	v_exp_f32_e32 v203, v211
	s_waitcnt lgkmcnt(0)
	v_pk_mul_f32 v[196:197], v[238:239], v[196:197]
	ds_write2st64_b32 v139, v194, v195 offset0:196 offset1:198
	ds_write_b32 v141, v197
	v_exp_f32_e32 v122, v122
	v_pk_add_f32 v[194:195], v[202:203], 1.0 op_sel_hi:[1,0]
	v_pk_fma_f32 v[202:203], v[208:209], s[4:5], v[128:129] op_sel_hi:[1,0,1] neg_lo:[1,0,0] neg_hi:[1,0,0]
	v_rcp_f32_e32 v194, v194
	v_rcp_f32_e32 v195, v195
	v_exp_f32_e32 v202, v202
	v_exp_f32_e32 v203, v203
	v_pk_mul_f32 v[194:195], v[130:131], v[194:195]
	v_exp_f32_e32 v123, v123
	v_exp_f32_e32 v194, v194
	v_exp_f32_e32 v195, v195
	v_pk_add_f32 v[202:203], v[202:203], 1.0 op_sel_hi:[1,0]
	v_pk_add_f32 v[122:123], v[122:123], 1.0 op_sel_hi:[1,0]
	v_rcp_f32_e32 v202, v202
	v_pk_fma_f32 v[206:207], v[194:195], v[194:195], 1.0 op_sel_hi:[1,1,0] neg_lo:[1,0,0] neg_hi:[1,0,0]
	v_rcp_f32_e32 v203, v203
	v_sqrt_f32_e32 v206, v206
	v_sqrt_f32_e32 v207, v207
	v_rcp_f32_e32 v122, v122
	v_rcp_f32_e32 v123, v123
	v_exp_f32_e32 v118, v118
	v_pk_mul_f32 v[202:203], v[202:203], v[206:207]
	v_exp_f32_e32 v119, v119
	v_pk_mul_f32 v[202:203], v[240:241], v[202:203]
	ds_write2st64_b32 v139, v194, v195 offset0:200 offset1:202
	ds_write_b32 v142, v202
	ds_write_b32 v143, v203
	v_pk_add_f32 v[194:195], v[198:199], 1.0 op_sel_hi:[1,0]
	v_pk_fma_f32 v[198:199], v[214:215], s[4:5], v[128:129] op_sel_hi:[1,0,1] neg_lo:[1,0,0] neg_hi:[1,0,0]
	v_rcp_f32_e32 v194, v194
	v_rcp_f32_e32 v195, v195
	v_exp_f32_e32 v198, v198
	v_exp_f32_e32 v199, v199
	v_pk_mul_f32 v[194:195], v[130:131], v[194:195]
	v_pk_mul_f32 v[122:123], v[130:131], v[122:123]
	v_exp_f32_e32 v194, v194
	v_exp_f32_e32 v195, v195
	v_pk_add_f32 v[198:199], v[198:199], 1.0 op_sel_hi:[1,0]
	v_exp_f32_e32 v122, v122
	v_rcp_f32_e32 v198, v198
	v_pk_fma_f32 v[202:203], v[194:195], v[194:195], 1.0 op_sel_hi:[1,1,0] neg_lo:[1,0,0] neg_hi:[1,0,0]
	v_rcp_f32_e32 v199, v199
	v_sqrt_f32_e32 v202, v202
	v_sqrt_f32_e32 v203, v203
	v_exp_f32_e32 v123, v123
	v_pk_add_f32 v[118:119], v[118:119], 1.0 op_sel_hi:[1,0]
	v_pk_fma_f32 v[124:125], v[124:125], s[4:5], v[90:91] op_sel_hi:[1,0,1] neg_lo:[1,0,0] neg_hi:[1,0,0]
	v_pk_mul_f32 v[198:199], v[198:199], v[202:203]
	v_rcp_f32_e32 v118, v118
	v_pk_mul_f32 v[198:199], v[242:243], v[198:199]
	ds_write2st64_b32 v139, v194, v195 offset0:228 offset1:230
	ds_write_b32 v144, v198
	ds_write_b32 v145, v199
	v_pk_add_f32 v[194:195], v[200:201], 1.0 op_sel_hi:[1,0]
	v_pk_fma_f32 v[198:199], v[216:217], s[4:5], v[128:129] op_sel_hi:[1,0,1] neg_lo:[1,0,0] neg_hi:[1,0,0]
	v_rcp_f32_e32 v194, v194
	v_rcp_f32_e32 v195, v195
	v_exp_f32_e32 v198, v198
	v_exp_f32_e32 v199, v199
	v_pk_mul_f32 v[194:195], v[130:131], v[194:195]
	v_rcp_f32_e32 v119, v119
	v_exp_f32_e32 v194, v194
	v_exp_f32_e32 v195, v195
	v_pk_add_f32 v[198:199], v[198:199], 1.0 op_sel_hi:[1,0]
	v_exp_f32_e32 v124, v124
	v_rcp_f32_e32 v198, v198
	v_pk_fma_f32 v[200:201], v[194:195], v[194:195], 1.0 op_sel_hi:[1,1,0] neg_lo:[1,0,0] neg_hi:[1,0,0]
	v_rcp_f32_e32 v199, v199
	v_sqrt_f32_e32 v200, v200
	v_sqrt_f32_e32 v201, v201
	v_exp_f32_e32 v125, v125
	v_pk_fma_f32 v[114:115], v[114:115], s[4:5], v[90:91] op_sel_hi:[1,0,1] neg_lo:[1,0,0] neg_hi:[1,0,0]
	v_pk_fma_f32 v[120:121], v[120:121], s[4:5], v[128:129] op_sel_hi:[1,0,1] neg_lo:[1,0,0] neg_hi:[1,0,0]
	v_pk_mul_f32 v[198:199], v[198:199], v[200:201]
	v_exp_f32_e32 v114, v114
	v_pk_mul_f32 v[198:199], v[198:199], v[244:245]
	ds_write2st64_b32 v139, v194, v195 offset0:232 offset1:234
	ds_write_b32 v146, v198
	ds_write_b32 v147, v199
	v_pk_fma_f32 v[194:195], v[122:123], v[122:123], 1.0 op_sel_hi:[1,1,0] neg_lo:[1,0,0] neg_hi:[1,0,0]
	v_sqrt_f32_e32 v194, v194
	v_sqrt_f32_e32 v195, v195
	ds_write_b32 v140, v196
	ds_write_b32 v148, v122
	v_exp_f32_e32 v115, v115
	v_pk_mul_f32 v[118:119], v[118:119], v[194:195]
	v_exp_f32_e32 v120, v120
	v_pk_mul_f32 v[118:119], v[118:119], v[246:247]
	ds_write_b32 v149, v123
	ds_write_b32 v150, v118
	ds_write_b32 v151, v119
	v_pk_add_f32 v[118:119], v[124:125], 1.0 op_sel_hi:[1,0]
	v_exp_f32_e32 v121, v121
	v_rcp_f32_e32 v118, v118
	v_rcp_f32_e32 v119, v119
	v_pk_add_f32 v[114:115], v[114:115], 1.0 op_sel_hi:[1,0]
	v_pk_add_f32 v[120:121], v[120:121], 1.0 op_sel_hi:[1,0]
	v_rcp_f32_e32 v114, v114
	v_pk_mul_f32 v[118:119], v[130:131], v[118:119]
	v_rcp_f32_e32 v115, v115
	v_exp_f32_e32 v118, v118
	v_exp_f32_e32 v119, v119
	v_rcp_f32_e32 v120, v120
	v_rcp_f32_e32 v121, v121
	v_pk_fma_f32 v[122:123], v[118:119], v[118:119], 1.0 op_sel_hi:[1,1,0] neg_lo:[1,0,0] neg_hi:[1,0,0]
	v_pk_fma_f32 v[110:111], v[110:111], s[4:5], v[128:129] op_sel_hi:[1,0,1] neg_lo:[1,0,0] neg_hi:[1,0,0]
	v_sqrt_f32_e32 v122, v122
	v_sqrt_f32_e32 v123, v123
	v_pk_mul_f32 v[114:115], v[130:131], v[114:115]
	v_exp_f32_e32 v110, v110
	v_exp_f32_e32 v111, v111
	v_exp_f32_e32 v114, v114
	v_exp_f32_e32 v115, v115
	v_pk_mul_f32 v[120:121], v[120:121], v[122:123]
	ds_write_b32 v152, v118
	v_pk_mul_f32 v[120:121], v[120:121], v[248:249]
	ds_write_b32 v153, v119
	ds_write_b32 v154, v120
	ds_write_b32 v155, v121
	v_pk_add_f32 v[110:111], v[110:111], 1.0 op_sel_hi:[1,0]
	v_pk_fma_f32 v[118:119], v[114:115], v[114:115], 1.0 op_sel_hi:[1,1,0] neg_lo:[1,0,0] neg_hi:[1,0,0]
	v_rcp_f32_e32 v110, v110
	v_rcp_f32_e32 v111, v111
	v_sqrt_f32_e32 v118, v118
	v_sqrt_f32_e32 v119, v119
	v_pk_fma_f32 v[116:117], v[116:117], s[4:5], v[90:91] op_sel_hi:[1,0,1] neg_lo:[1,0,0] neg_hi:[1,0,0]
	ds_write_b32 v156, v114
	v_exp_f32_e32 v116, v116
	v_exp_f32_e32 v117, v117
	v_pk_mul_f32 v[110:111], v[110:111], v[118:119]
	v_pk_fma_f32 v[112:113], v[112:113], s[4:5], v[128:129] op_sel_hi:[1,0,1] neg_lo:[1,0,0] neg_hi:[1,0,0]
	v_pk_mul_f32 v[110:111], v[110:111], v[250:251]
	ds_write_b32 v157, v115
	ds_write_b32 v158, v110
	ds_write_b32 v159, v111
	v_pk_add_f32 v[110:111], v[116:117], 1.0 op_sel_hi:[1,0]
	v_exp_f32_e32 v112, v112
	v_rcp_f32_e32 v110, v110
	v_rcp_f32_e32 v111, v111
	v_exp_f32_e32 v113, v113
	v_pk_mul_f32 v[110:111], v[130:131], v[110:111]
	s_nop 0
	v_exp_f32_e32 v110, v110
	v_exp_f32_e32 v111, v111
	v_pk_add_f32 v[112:113], v[112:113], 1.0 op_sel_hi:[1,0]
	v_pk_fma_f32 v[114:115], v[110:111], v[110:111], 1.0 op_sel_hi:[1,1,0] neg_lo:[1,0,0] neg_hi:[1,0,0]
	v_rcp_f32_e32 v112, v112
	v_rcp_f32_e32 v113, v113
	v_sqrt_f32_e32 v114, v114
	v_sqrt_f32_e32 v115, v115
	s_nop 0
	v_pk_mul_f32 v[112:113], v[112:113], v[114:115]
	v_pk_mul_f32 v[112:113], v[112:113], v[252:253]
	ds_write_b32 v160, v110
	ds_write_b32 v161, v111
	ds_write_b32 v162, v112
	ds_write_b32 v163, v113
	s_waitcnt lgkmcnt(0)
	s_barrier
	ds_read2st64_b32 v[110:111], v164 offset0:196 offset1:198
	ds_read2st64_b32 v[112:113], v164 offset0:200 offset1:202
	ds_read_b32 v88, v165
	ds_read_b32 v109, v166
	ds_read_b32 v114, v167
	ds_read_b32 v115, v168
	ds_read_b32 v116, v169
	ds_read_b32 v117, v170
	ds_read_b32 v118, v171
	ds_read_b32 v119, v172
	s_waitcnt lgkmcnt(7)
	v_fmac_f32_e32 v88, 0, v110
	s_waitcnt lgkmcnt(6)
	v_fmac_f32_e32 v109, v88, v111
	v_mul_f32_e32 v88, v110, v111
	ds_read2st64_b32 v[110:111], v164 offset0:204 offset1:206
	s_waitcnt lgkmcnt(6)
	v_fmac_f32_e32 v114, v109, v112
	v_mul_f32_e32 v88, v88, v112
	s_waitcnt lgkmcnt(5)
	v_fmac_f32_e32 v115, v114, v113
	v_mul_f32_e32 v88, v88, v113
	ds_read2st64_b32 v[112:113], v164 offset0:208 offset1:210
	s_waitcnt lgkmcnt(1)
	v_fmac_f32_e32 v116, v115, v110
	v_mul_f32_e32 v88, v88, v110
	v_fmac_f32_e32 v117, v116, v111
	v_mul_f32_e32 v88, v88, v111
	s_waitcnt lgkmcnt(0)
	v_fmac_f32_e32 v118, v117, v112
	v_mul_f32_e32 v88, v88, v112
	v_fmac_f32_e32 v119, v118, v113
	v_mul_f32_e32 v88, v88, v113
	ds_read2st64_b32 v[110:111], v164 offset0:212 offset1:214
	ds_read2st64_b32 v[112:113], v164 offset0:216 offset1:218
	ds_read_b32 v109, v173
	ds_read_b32 v114, v174
	ds_read_b32 v115, v175
	ds_read_b32 v116, v176
	ds_read_b32 v117, v177
	ds_read_b32 v118, v178
	ds_read_b32 v120, v179
	ds_read_b32 v121, v180
	s_waitcnt lgkmcnt(7)
	v_fmac_f32_e32 v109, v119, v110
	v_mul_f32_e32 v88, v88, v110
	s_waitcnt lgkmcnt(6)
	v_fmac_f32_e32 v114, v109, v111
	v_mul_f32_e32 v88, v88, v111
	ds_read2st64_b32 v[110:111], v164 offset0:220 offset1:222
	s_waitcnt lgkmcnt(6)
	v_fmac_f32_e32 v115, v114, v112
	v_mul_f32_e32 v88, v88, v112
	s_waitcnt lgkmcnt(5)
	v_fmac_f32_e32 v116, v115, v113
	v_mul_f32_e32 v88, v88, v113
	ds_read2st64_b32 v[112:113], v164 offset0:224 offset1:226
	s_waitcnt lgkmcnt(1)
	v_mul_f32_e32 v88, v88, v110
	v_fmac_f32_e32 v117, v116, v110
	v_mul_f32_e32 v88, v88, v111
	v_fmac_f32_e32 v118, v117, v111
	s_waitcnt lgkmcnt(0)
	v_mul_f32_e32 v88, v88, v112
	v_fmac_f32_e32 v120, v118, v112
	v_mul_f32_e32 v88, v88, v113
	v_fmac_f32_e32 v121, v120, v113
	ds_write_b32 v136, v88
	ds_write_b32 v137, v121
	s_waitcnt lgkmcnt(0)
	s_barrier
	s_and_saveexec_b64 s[0:1], vcc
	s_cbranch_execz .LBB0_282
	ds_read_b32 v88, v181
	ds_read_b32 v109, v182
	ds_read_b32 v110, v183
	ds_read_b32 v111, v184
	ds_read_b32 v112, v185
	ds_read_b32 v113, v186
	ds_read_b32 v114, v187
	ds_read_b32 v115, v189
	s_and_b32 s5, s2, 0x60
	s_add_i32 s5, s5, s87
	s_waitcnt lgkmcnt(6)
	v_fmac_f32_e32 v109, 0, v88
	s_waitcnt lgkmcnt(5)
	v_mul_f32_e32 v88, v88, v110
	s_and_b32 s6, s2, 0x80
	s_waitcnt lgkmcnt(3)
	v_mul_f32_e32 v88, v88, v112
	s_add_i32 s5, s5, s6
	v_fmac_f32_e32 v111, v109, v110
	s_waitcnt lgkmcnt(1)
	v_mul_f32_e32 v109, v88, v114
	v_lshl_or_b32 v88, s5, 10, v190
	v_fmac_f32_e32 v113, v111, v112
	v_lshlrev_b64 v[110:111], 2, v[88:89]
	s_waitcnt lgkmcnt(0)
	v_fmac_f32_e32 v115, v113, v114
	v_lshl_add_u64 v[112:113], s[80:81], 0, v[110:111]
	v_lshl_add_u64 v[110:111], s[82:83], 0, v[110:111]
	s_waitcnt vmcnt(0)
	global_store_dword v[112:113], v109, off
	global_store_dword v[110:111], v115, off
	s_or_b64 exec, exec, s[0:1]
	s_add_i32 s2, s2, 32
	s_addk_i32 s3, 0x800
	s_cmpk_lg_i32 s2, 0x100
	s_cbranch_scc0 .LBB0_303
	s_branch .Llru1_waited

.LBB0_646:
	s_waitcnt lgkmcnt(0)
	s_barrier
	ds_read_b128 v[120:123], v154
	ds_read_b128 v[124:127], v154 offset:4352
	ds_read_b128 v[132:135], v154 offset:8704
	ds_read_b128 v[216:219], v154 offset:13056
	s_waitcnt lgkmcnt(3)
	v_mfma_f32_16x16x32_bf16 v[128:131], v[120:123], v[0:3], 0
	v_mfma_f32_16x16x32_bf16 v[120:123], v[120:123], v[8:11], 0
	ds_read_b128 v[224:227], v154 offset:64
	s_waitcnt lgkmcnt(3)
	v_mfma_f32_16x16x32_bf16 v[220:223], v[124:127], v[0:3], 0
	v_mfma_f32_16x16x32_bf16 v[124:127], v[124:127], v[8:11], 0
	ds_read_b128 v[232:235], v154 offset:4416
	s_waitcnt lgkmcnt(3)
	v_mfma_f32_16x16x32_bf16 v[228:231], v[132:135], v[0:3], 0
	v_mfma_f32_16x16x32_bf16 v[132:135], v[132:135], v[8:11], 0
	ds_read_b128 v[240:243], v154 offset:8768
	s_waitcnt lgkmcnt(3)
	v_mfma_f32_16x16x32_bf16 v[236:239], v[216:219], v[0:3], 0
	v_mfma_f32_16x16x32_bf16 v[216:219], v[216:219], v[8:11], 0
	ds_read_b128 v[244:247], v154 offset:13120
	s_waitcnt lgkmcnt(3)
	v_mfma_f32_16x16x32_bf16 v[128:131], v[224:227], v[4:7], v[128:131]
	v_mfma_f32_16x16x32_bf16 v[120:123], v[224:227], v[12:15], v[120:123]
	ds_read_b128 v[224:227], v154 offset:128
	s_waitcnt lgkmcnt(3)
	v_mfma_f32_16x16x32_bf16 v[220:223], v[232:235], v[4:7], v[220:223]
	v_mfma_f32_16x16x32_bf16 v[124:127], v[232:235], v[12:15], v[124:127]
	ds_read_b128 v[232:235], v154 offset:4480
	s_waitcnt lgkmcnt(3)
	v_mfma_f32_16x16x32_bf16 v[228:231], v[240:243], v[4:7], v[228:231]
	v_mfma_f32_16x16x32_bf16 v[132:135], v[240:243], v[12:15], v[132:135]
	ds_read_b128 v[240:243], v154 offset:8832
	s_waitcnt lgkmcnt(3)
	v_mfma_f32_16x16x32_bf16 v[236:239], v[244:247], v[4:7], v[236:239]
	v_mfma_f32_16x16x32_bf16 v[216:219], v[244:247], v[12:15], v[216:219]
	ds_read_b128 v[244:247], v154 offset:13184
	s_waitcnt lgkmcnt(3)
	v_mfma_f32_16x16x32_bf16 v[128:131], v[224:227], v[16:19], v[128:131]
	v_mfma_f32_16x16x32_bf16 v[120:123], v[224:227], v[24:27], v[120:123]
	ds_read_b128 v[224:227], v154 offset:192
	s_waitcnt lgkmcnt(3)
	v_mfma_f32_16x16x32_bf16 v[220:223], v[232:235], v[16:19], v[220:223]
	v_mfma_f32_16x16x32_bf16 v[124:127], v[232:235], v[24:27], v[124:127]
	ds_read_b128 v[232:235], v154 offset:4544
	s_waitcnt lgkmcnt(3)
	v_mfma_f32_16x16x32_bf16 v[228:231], v[240:243], v[16:19], v[228:231]
	v_mfma_f32_16x16x32_bf16 v[240:243], v[240:243], v[24:27], v[132:135]
	ds_read_b128 v[248:251], v154 offset:8896
	s_waitcnt lgkmcnt(3)
	v_mfma_f32_16x16x32_bf16 v[236:239], v[244:247], v[16:19], v[236:239]
	v_mfma_f32_16x16x32_bf16 v[216:219], v[244:247], v[24:27], v[216:219]
	ds_read_b128 v[162:165], v154 offset:13248
	s_waitcnt lgkmcnt(3)
	v_mfma_f32_16x16x32_bf16 v[244:247], v[224:227], v[20:23], v[128:131]
	v_mfma_f32_16x16x32_bf16 v[224:227], v[224:227], v[28:31], v[120:123]
	s_waitcnt lgkmcnt(2)
	v_mfma_f32_16x16x32_bf16 v[220:223], v[232:235], v[20:23], v[220:223]
	v_mfma_f32_16x16x32_bf16 v[232:235], v[232:235], v[28:31], v[124:127]
	s_waitcnt lgkmcnt(1)
	v_mfma_f32_16x16x32_bf16 v[132:135], v[248:251], v[20:23], v[228:231]
	v_mfma_f32_16x16x32_bf16 v[128:131], v[248:251], v[28:31], v[240:243]
	s_waitcnt lgkmcnt(0)
	v_mfma_f32_16x16x32_bf16 v[124:127], v[162:165], v[20:23], v[236:239]
	v_mfma_f32_16x16x32_bf16 v[120:123], v[162:165], v[28:31], v[216:219]
	ds_read2st64_b32 v[240:241], v159 offset0:68 offset1:70
	ds_read2st64_b32 v[242:243], v159 offset0:72 offset1:74
	ds_read2st64_b32 v[248:249], v159 offset0:100 offset1:102
	ds_read2st64_b32 v[250:251], v159 offset0:104 offset1:106
	v_fma_f32 v110, -v244, s16, v138
	v_fma_f32 v111, -v245, s16, v139
	v_pk_fma_f32 v[162:163], v[224:225], s[16:17], v[140:141] op_sel_hi:[1,0,1] neg_lo:[1,0,0] neg_hi:[1,0,0]
	v_exp_f32_e32 v110, v110
	v_exp_f32_e32 v111, v111
	v_exp_f32_e32 v162, v162
	v_exp_f32_e32 v163, v163
	v_pk_add_f32 v[110:111], v[110:111], 1.0 op_sel_hi:[1,0]
	v_pk_fma_f32 v[218:219], v[246:247], s[16:17], v[138:139] op_sel_hi:[1,0,1] neg_lo:[1,0,0] neg_hi:[1,0,0]
	v_rcp_f32_e32 v110, v110
	v_rcp_f32_e32 v111, v111
	v_pk_add_f32 v[162:163], v[162:163], 1.0 op_sel_hi:[1,0]
	v_pk_fma_f32 v[132:133], v[132:133], s[16:17], v[138:139] op_sel_hi:[1,0,1] neg_lo:[1,0,0] neg_hi:[1,0,0]
	v_rcp_f32_e32 v162, v162
	v_pk_mul_f32 v[110:111], v[142:143], v[110:111]
	v_rcp_f32_e32 v163, v163
	v_exp_f32_e32 v110, v110
	v_exp_f32_e32 v111, v111
	v_exp_f32_e32 v132, v132
	v_exp_f32_e32 v133, v133
	v_pk_fma_f32 v[128:129], v[128:129], s[16:17], v[140:141] op_sel_hi:[1,0,1] neg_lo:[1,0,0] neg_hi:[1,0,0]
	v_pk_fma_f32 v[164:165], v[110:111], v[110:111], 1.0 op_sel_hi:[1,1,0] neg_lo:[1,0,0] neg_hi:[1,0,0]
	v_exp_f32_e32 v128, v128
	v_sqrt_f32_e32 v164, v164
	v_sqrt_f32_e32 v165, v165
	v_exp_f32_e32 v129, v129
	v_pk_fma_f32 v[124:125], v[124:125], s[16:17], v[138:139] op_sel_hi:[1,0,1] neg_lo:[1,0,0] neg_hi:[1,0,0]
	v_pk_fma_f32 v[120:121], v[120:121], s[16:17], v[140:141] op_sel_hi:[1,0,1] neg_lo:[1,0,0] neg_hi:[1,0,0]
	v_pk_mul_f32 v[162:163], v[162:163], v[164:165]
	v_exp_f32_e32 v164, v218
	v_exp_f32_e32 v165, v219
	s_waitcnt lgkmcnt(0)
	v_pk_mul_f32 v[162:163], v[240:241], v[162:163]
	ds_write2st64_b32 v159, v110, v111 offset0:196 offset1:198
	ds_write_b32 v161, v163
	v_pk_add_f32 v[110:111], v[164:165], 1.0 op_sel_hi:[1,0]
	v_pk_fma_f32 v[164:165], v[226:227], s[16:17], v[140:141] op_sel_hi:[1,0,1] neg_lo:[1,0,0] neg_hi:[1,0,0]
	v_rcp_f32_e32 v110, v110
	v_rcp_f32_e32 v111, v111
	v_exp_f32_e32 v164, v164
	v_exp_f32_e32 v165, v165
	v_pk_add_f32 v[128:129], v[128:129], 1.0 op_sel_hi:[1,0]
	v_pk_mul_f32 v[110:111], v[142:143], v[110:111]
	v_rcp_f32_e32 v128, v128
	v_exp_f32_e32 v110, v110
	v_exp_f32_e32 v111, v111
	v_pk_add_f32 v[164:165], v[164:165], 1.0 op_sel_hi:[1,0]
	v_rcp_f32_e32 v129, v129
	v_rcp_f32_e32 v164, v164
	v_pk_fma_f32 v[216:217], v[110:111], v[110:111], 1.0 op_sel_hi:[1,1,0] neg_lo:[1,0,0] neg_hi:[1,0,0]
	v_rcp_f32_e32 v165, v165
	v_sqrt_f32_e32 v216, v216
	v_sqrt_f32_e32 v217, v217
	v_exp_f32_e32 v124, v124
	v_exp_f32_e32 v125, v125
	v_exp_f32_e32 v120, v120
	v_pk_mul_f32 v[164:165], v[164:165], v[216:217]
	v_pk_fma_f32 v[216:217], v[220:221], s[16:17], v[138:139] op_sel_hi:[1,0,1] neg_lo:[1,0,0] neg_hi:[1,0,0]
	v_pk_mul_f32 v[164:165], v[242:243], v[164:165]
	v_exp_f32_e32 v216, v216
	v_exp_f32_e32 v217, v217
	ds_write2st64_b32 v159, v110, v111 offset0:200 offset1:202
	ds_write_b32 v215, v164
	ds_write_b32 v252, v165
	v_pk_fma_f32 v[164:165], v[232:233], s[16:17], v[140:141] op_sel_hi:[1,0,1] neg_lo:[1,0,0] neg_hi:[1,0,0]
	v_pk_add_f32 v[110:111], v[216:217], 1.0 op_sel_hi:[1,0]
	v_exp_f32_e32 v164, v164
	v_rcp_f32_e32 v110, v110
	v_rcp_f32_e32 v111, v111
	v_exp_f32_e32 v165, v165
	v_exp_f32_e32 v121, v121
	v_pk_mul_f32 v[110:111], v[142:143], v[110:111]
	s_nop 0
	v_exp_f32_e32 v110, v110
	v_exp_f32_e32 v111, v111
	v_pk_add_f32 v[164:165], v[164:165], 1.0 op_sel_hi:[1,0]
	v_pk_add_f32 v[120:121], v[120:121], 1.0 op_sel_hi:[1,0]
	v_rcp_f32_e32 v164, v164
	v_pk_fma_f32 v[216:217], v[110:111], v[110:111], 1.0 op_sel_hi:[1,1,0] neg_lo:[1,0,0] neg_hi:[1,0,0]
	v_rcp_f32_e32 v165, v165
	v_sqrt_f32_e32 v216, v216
	v_sqrt_f32_e32 v217, v217
	v_rcp_f32_e32 v120, v120
	v_rcp_f32_e32 v121, v121
	v_pk_mul_f32 v[164:165], v[164:165], v[216:217]
	v_pk_fma_f32 v[216:217], v[222:223], s[16:17], v[138:139] op_sel_hi:[1,0,1] neg_lo:[1,0,0] neg_hi:[1,0,0]
	v_pk_mul_f32 v[164:165], v[248:249], v[164:165]
	v_exp_f32_e32 v216, v216
	v_exp_f32_e32 v217, v217
	ds_write2st64_b32 v159, v110, v111 offset0:228 offset1:230
	ds_write_b32 v253, v164
	ds_write_b32 v254, v165
	v_pk_fma_f32 v[164:165], v[234:235], s[16:17], v[140:141] op_sel_hi:[1,0,1] neg_lo:[1,0,0] neg_hi:[1,0,0]
	v_pk_add_f32 v[110:111], v[216:217], 1.0 op_sel_hi:[1,0]
	v_exp_f32_e32 v164, v164
	v_rcp_f32_e32 v110, v110
	v_rcp_f32_e32 v111, v111
	v_exp_f32_e32 v165, v165
	v_pk_mul_f32 v[110:111], v[142:143], v[110:111]
	s_nop 0
	v_exp_f32_e32 v110, v110
	v_exp_f32_e32 v111, v111
	v_pk_add_f32 v[164:165], v[164:165], 1.0 op_sel_hi:[1,0]
	v_pk_fma_f32 v[216:217], v[110:111], v[110:111], 1.0 op_sel_hi:[1,1,0] neg_lo:[1,0,0] neg_hi:[1,0,0]
	v_rcp_f32_e32 v164, v164
	v_rcp_f32_e32 v165, v165
	v_sqrt_f32_e32 v216, v216
	v_sqrt_f32_e32 v217, v217
	s_nop 0
	v_pk_mul_f32 v[164:165], v[164:165], v[216:217]
	v_pk_mul_f32 v[164:165], v[164:165], v[250:251]
	ds_read2st64_b32 v[240:241], v159 offset0:132 offset1:134
	ds_read2st64_b32 v[242:243], v159 offset0:136 offset1:138
	ds_read2st64_b32 v[248:249], v159 offset0:164 offset1:166
	ds_read2st64_b32 v[250:251], v159 offset0:168 offset1:170
	ds_write2st64_b32 v159, v110, v111 offset0:232 offset1:234
	ds_write_b32 v166, v164
	ds_write_b32 v167, v165
	v_pk_add_f32 v[110:111], v[132:133], 1.0 op_sel_hi:[1,0]
	v_rcp_f32_e32 v110, v110
	v_rcp_f32_e32 v111, v111
	ds_write_b32 v160, v162
	v_pk_mul_f32 v[110:111], v[142:143], v[110:111]
	s_nop 0
	v_exp_f32_e32 v110, v110
	v_exp_f32_e32 v111, v111
	ds_write_b32 v168, v110
	v_pk_fma_f32 v[132:133], v[110:111], v[110:111], 1.0 op_sel_hi:[1,1,0] neg_lo:[1,0,0] neg_hi:[1,0,0]
	s_nop 0
	v_sqrt_f32_e32 v132, v132
	v_sqrt_f32_e32 v133, v133
	s_nop 0
	v_pk_mul_f32 v[128:129], v[128:129], v[132:133]
	v_pk_fma_f32 v[132:133], v[134:135], s[16:17], v[138:139] op_sel_hi:[1,0,1] neg_lo:[1,0,0] neg_hi:[1,0,0]
	s_waitcnt lgkmcnt(5)
	v_pk_mul_f32 v[128:129], v[128:129], v[240:241]
	v_exp_f32_e32 v132, v132
	v_exp_f32_e32 v133, v133
	ds_write_b32 v169, v111
	ds_write_b32 v170, v128
	ds_write_b32 v171, v129
	v_pk_fma_f32 v[128:129], v[130:131], s[16:17], v[140:141] op_sel_hi:[1,0,1] neg_lo:[1,0,0] neg_hi:[1,0,0]
	v_pk_add_f32 v[110:111], v[132:133], 1.0 op_sel_hi:[1,0]
	s_nop 0
	v_rcp_f32_e32 v110, v110
	v_rcp_f32_e32 v111, v111
	v_exp_f32_e32 v128, v128
	v_exp_f32_e32 v129, v129
	v_pk_mul_f32 v[110:111], v[142:143], v[110:111]
	v_pk_add_f32 v[128:129], v[128:129], 1.0 op_sel_hi:[1,0]
	v_exp_f32_e32 v110, v110
	v_exp_f32_e32 v111, v111
	v_rcp_f32_e32 v128, v128
	v_rcp_f32_e32 v129, v129
	ds_write_b32 v172, v110
	v_pk_fma_f32 v[130:131], v[110:111], v[110:111], 1.0 op_sel_hi:[1,1,0] neg_lo:[1,0,0] neg_hi:[1,0,0]
	s_nop 0
	v_sqrt_f32_e32 v130, v130
	v_sqrt_f32_e32 v131, v131
	s_nop 0
	v_pk_mul_f32 v[128:129], v[128:129], v[130:131]
	v_pk_mul_f32 v[128:129], v[128:129], v[242:243]
	ds_write_b32 v173, v111
	ds_write_b32 v174, v128
	ds_write_b32 v175, v129
	v_pk_add_f32 v[110:111], v[124:125], 1.0 op_sel_hi:[1,0]
	v_rcp_f32_e32 v110, v110
	v_rcp_f32_e32 v111, v111
	s_nop 0
	v_pk_mul_f32 v[110:111], v[142:143], v[110:111]
	s_nop 0
	v_exp_f32_e32 v110, v110
	v_exp_f32_e32 v111, v111
	ds_write_b32 v176, v110
	v_pk_fma_f32 v[124:125], v[110:111], v[110:111], 1.0 op_sel_hi:[1,1,0] neg_lo:[1,0,0] neg_hi:[1,0,0]
	s_nop 0
	v_sqrt_f32_e32 v124, v124
	v_sqrt_f32_e32 v125, v125
	s_nop 0
	v_pk_mul_f32 v[120:121], v[120:121], v[124:125]
	v_pk_fma_f32 v[124:125], v[126:127], s[16:17], v[138:139] op_sel_hi:[1,0,1] neg_lo:[1,0,0] neg_hi:[1,0,0]
	v_pk_mul_f32 v[120:121], v[120:121], v[248:249]
	v_exp_f32_e32 v124, v124
	v_exp_f32_e32 v125, v125
	ds_write_b32 v177, v111
	ds_write_b32 v178, v120
	ds_write_b32 v179, v121
	v_pk_fma_f32 v[120:121], v[122:123], s[16:17], v[140:141] op_sel_hi:[1,0,1] neg_lo:[1,0,0] neg_hi:[1,0,0]
	v_pk_add_f32 v[110:111], v[124:125], 1.0 op_sel_hi:[1,0]
	s_nop 0
	v_rcp_f32_e32 v110, v110
	v_rcp_f32_e32 v111, v111
	v_exp_f32_e32 v120, v120
	v_exp_f32_e32 v121, v121
	v_pk_mul_f32 v[110:111], v[142:143], v[110:111]
	v_pk_add_f32 v[120:121], v[120:121], 1.0 op_sel_hi:[1,0]
	v_exp_f32_e32 v110, v110
	v_exp_f32_e32 v111, v111
	v_rcp_f32_e32 v120, v120
	v_rcp_f32_e32 v121, v121
	v_pk_fma_f32 v[122:123], v[110:111], v[110:111], 1.0 op_sel_hi:[1,1,0] neg_lo:[1,0,0] neg_hi:[1,0,0]
	s_nop 0
	v_sqrt_f32_e32 v122, v122
	v_sqrt_f32_e32 v123, v123
	s_nop 0
	v_pk_mul_f32 v[120:121], v[120:121], v[122:123]
	v_pk_mul_f32 v[120:121], v[120:121], v[250:251]
	ds_write_b32 v180, v110
	ds_write_b32 v181, v111
	ds_write_b32 v182, v120
	ds_write_b32 v183, v121
	s_waitcnt lgkmcnt(0)
	s_barrier
	ds_read2st64_b32 v[110:111], v184 offset0:196 offset1:198
	ds_read2st64_b32 v[120:121], v184 offset0:200 offset1:202
	ds_read_b32 v88, v185
	ds_read_b32 v109, v186
	ds_read_b32 v122, v187
	ds_read_b32 v123, v189
	ds_read_b32 v124, v190
	ds_read_b32 v125, v191
	ds_read_b32 v126, v192
	ds_read_b32 v127, v193
	s_waitcnt lgkmcnt(7)
	v_fmac_f32_e32 v88, 0, v110
	s_waitcnt lgkmcnt(6)
	v_fmac_f32_e32 v109, v88, v111
	v_mul_f32_e32 v88, v110, v111
	ds_read2st64_b32 v[110:111], v184 offset0:204 offset1:206
	s_waitcnt lgkmcnt(6)
	v_fmac_f32_e32 v122, v109, v120
	v_mul_f32_e32 v88, v88, v120
	s_waitcnt lgkmcnt(5)
	v_fmac_f32_e32 v123, v122, v121
	v_mul_f32_e32 v88, v88, v121
	ds_read2st64_b32 v[120:121], v184 offset0:208 offset1:210
	s_waitcnt lgkmcnt(1)
	v_fmac_f32_e32 v124, v123, v110
	v_mul_f32_e32 v88, v88, v110
	v_fmac_f32_e32 v125, v124, v111
	v_mul_f32_e32 v88, v88, v111
	s_waitcnt lgkmcnt(0)
	v_fmac_f32_e32 v126, v125, v120
	v_mul_f32_e32 v88, v88, v120
	v_fmac_f32_e32 v127, v126, v121
	v_mul_f32_e32 v88, v88, v121
	ds_read2st64_b32 v[110:111], v184 offset0:212 offset1:214
	ds_read2st64_b32 v[120:121], v184 offset0:216 offset1:218
	ds_read_b32 v109, v194
	ds_read_b32 v122, v195
	ds_read_b32 v123, v196
	ds_read_b32 v124, v197
	ds_read_b32 v125, v198
	ds_read_b32 v126, v199
	ds_read_b32 v128, v200
	ds_read_b32 v129, v201
	s_waitcnt lgkmcnt(7)
	v_fmac_f32_e32 v109, v127, v110
	v_mul_f32_e32 v88, v88, v110
	s_waitcnt lgkmcnt(6)
	v_fmac_f32_e32 v122, v109, v111
	v_mul_f32_e32 v88, v88, v111
	ds_read2st64_b32 v[110:111], v184 offset0:220 offset1:222
	s_waitcnt lgkmcnt(6)
	v_fmac_f32_e32 v123, v122, v120
	v_mul_f32_e32 v88, v88, v120
	s_waitcnt lgkmcnt(5)
	v_fmac_f32_e32 v124, v123, v121
	v_mul_f32_e32 v88, v88, v121
	ds_read2st64_b32 v[120:121], v184 offset0:224 offset1:226
	s_waitcnt lgkmcnt(1)
	v_mul_f32_e32 v88, v88, v110
	v_fmac_f32_e32 v125, v124, v110
	v_mul_f32_e32 v88, v88, v111
	v_fmac_f32_e32 v126, v125, v111
	s_waitcnt lgkmcnt(0)
	v_mul_f32_e32 v88, v88, v120
	v_fmac_f32_e32 v128, v126, v120
	v_mul_f32_e32 v88, v88, v121
	v_fmac_f32_e32 v129, v128, v121
	ds_write_b32 v155, v88
	ds_write_b32 v156, v129
	s_waitcnt lgkmcnt(0)
	s_barrier
	ds_read_b32 v88, v212
	s_and_saveexec_b64 s[2:3], s[0:1]
	s_cbranch_execnz .LBB0_652
	s_or_b64 exec, exec, s[2:3]
	s_and_saveexec_b64 s[2:3], s[4:5]
	s_cbranch_execnz .LBB0_653
